# K-finalize loop: conservative loop-header vmcnt(0) removed so the next trip's loads issue while the previous trip's stores drain (waitcnt placement)
# baseline (speedup 1.0000x reference)
; __device__ __forceinline__ float sq4(f32x4 a) { return (a.x * a.x + a.y * a.y) + (a.z * a.z + a.w * a.w); }
; __device__ __forceinline__ void finalize_phase(const Params& p, LAS unsigned char* lds, int G) {
;     ...
;     for (int rowb = gw; rowb < M; rowb += 8 * NGW) {
;         u32x4 kn8[8]; f32x2 kx1[8], kx2[8], csv[8], snv[8];
; #pragma unroll
;         for (int k = 0; k < 8; ++k) {
;             const int row = (rowb + k * NGW < M) ? rowb + k * NGW : rowb;
;             const bf16_t* kk = KVRAW + (size_t)row * 1024 + h * 128;
;             kn8[k] = *(const u32x4*)(kk + 8 * sub);
;             kx1[k] = *(const f32x2*)(KR + (size_t)row * 32 + 2 * sub); kx2[k] = *(const f32x2*)(KR + (size_t)row * 32 + 16 + 2 * sub);
;             csv[k] = *(const f32x2*)(COS + (size_t)row * 16 + 2 * sub); snv[k] = *(const f32x2*)(SIN + (size_t)row * 16 + 2 * sub);
;         }
; #pragma unroll
;         for (int k = 0; k < 8; ++k) {
;             const int row = rowb + k * NGW;
;             if (row < M) {
;                 const int b = row >> 12, s = row & 4095;
;                 const f32x2 cs = csv[k], sn = snv[k];
;                 const size_t orow = ((size_t)(b * 8 + h) * SEQ + s) * 96;
;                 {
;                     const u32x4 n8 = kn8[k];
;                     f32x4 a0 = {bflo(n8.x), bfhi(n8.x), bflo(n8.y), bfhi(n8.y)}, a1 = {bflo(n8.z), bfhi(n8.z), bflo(n8.w), bfhi(n8.w)};
;                     f32x2 x1 = kx1[k], x2 = kx2[k];
;                     float ss = sq4(a0) + sq4(a1) + (x1.x * x1.x + x1.y * x1.y) + (x2.x * x2.x + x2.y * x2.y);
;                     ss += __shfl_xor(ss, 1); ss += __shfl_xor(ss, 2); ss += __shfl_xor(ss, 4);
;                     const float r = 1.0f / sqrtf(ss * (1.f / 96.f) + EPS);
.LBB0_555:
	v_add_u32_e32 v129, s5, v38
	v_cmp_gt_i32_e64 s[50:51], s4, v129
	v_add_u32_e32 v128, s6, v38
	v_cmp_gt_i32_e64 s[48:49], s4, v128
	v_cndmask_b32_e64 v8, v38, v129, s[50:51]
	v_ashrrev_i32_e32 v9, 31, v8
	v_lshlrev_b64 v[10:11], 11, v[8:9]
	v_lshl_add_u64 v[10:11], v[46:47], 0, v[10:11]
	v_lshlrev_b64 v[12:13], 7, v[8:9]
	v_lshlrev_b64 v[8:9], 6, v[8:9]
	v_lshl_add_u64 v[12:13], v[52:53], 0, v[12:13]
	global_load_dwordx4 v[32:35], v[10:11], off
	global_load_dwordx2 v[110:111], v[12:13], off
	v_lshl_add_u64 v[10:11], v[48:49], 0, v[8:9]
	v_lshl_add_u64 v[8:9], v[50:51], 0, v[8:9]
	global_load_dwordx2 v[116:117], v[12:13], off offset:64
	global_load_dwordx2 v[112:113], v[10:11], off
	global_load_dwordx2 v[114:115], v[8:9], off
	v_cndmask_b32_e64 v8, v38, v128, s[48:49]
	v_ashrrev_i32_e32 v9, 31, v8
	s_mul_i32 s0, s3, 24
	v_lshlrev_b64 v[10:11], 11, v[8:9]
	v_lshlrev_b64 v[12:13], 7, v[8:9]
	v_add_u32_e32 v127, s0, v38
	v_lshl_add_u64 v[10:11], v[46:47], 0, v[10:11]
	v_lshl_add_u64 v[12:13], v[52:53], 0, v[12:13]
	v_lshlrev_b64 v[8:9], 6, v[8:9]
	v_cmp_gt_i32_e64 s[46:47], s4, v127
	global_load_dwordx4 v[28:31], v[10:11], off
	global_load_dwordx2 v[102:103], v[12:13], off
	v_lshl_add_u64 v[10:11], v[48:49], 0, v[8:9]
	v_lshl_add_u64 v[8:9], v[50:51], 0, v[8:9]
	global_load_dwordx2 v[108:109], v[12:13], off offset:64
	global_load_dwordx2 v[104:105], v[10:11], off
	global_load_dwordx2 v[106:107], v[8:9], off
	v_cndmask_b32_e64 v12, v38, v127, s[46:47]
	v_ashrrev_i32_e32 v13, 31, v12
	v_lshlrev_b64 v[8:9], 11, v[12:13]
	v_lshl_add_u64 v[14:15], v[46:47], 0, v[8:9]
	v_lshl_add_u64 v[8:9], s[92:93], 0, v[54:55]
	global_load_dwordx4 v[8:11], v[8:9], off
	v_lshl_add_u64 v[62:63], s[92:93], 0, v[58:59]
	s_mov_b32 s0, 0x2a00000
	v_add_co_u32_e32 v18, vcc, s0, v62
	v_lshl_add_u64 v[20:21], s[92:93], 0, v[56:57]
	s_nop 0
	v_addc_co_u32_e32 v19, vcc, 0, v63, vcc
	s_mov_b32 s0, 0x1f000000
	v_lshlrev_b64 v[16:17], 7, v[12:13]
	v_add_co_u32_e32 v20, vcc, s0, v20
	v_lshl_add_u64 v[16:17], v[52:53], 0, v[16:17]
	s_nop 0
	v_addc_co_u32_e32 v21, vcc, 0, v21, vcc
	global_load_dwordx2 v[130:131], v[18:19], off
	global_load_dwordx2 v[132:133], v[20:21], off offset:64
	global_load_dwordx2 v[134:135], v[20:21], off
	global_load_dwordx4 v[24:27], v[14:15], off
	global_load_dwordx2 v[96:97], v[16:17], off
	v_lshlrev_b64 v[12:13], 6, v[12:13]
	v_add_u32_e32 v126, s7, v38
	v_lshl_add_u64 v[14:15], v[48:49], 0, v[12:13]
	v_lshl_add_u64 v[12:13], v[50:51], 0, v[12:13]
	v_cmp_gt_i32_e64 s[44:45], s4, v126
	global_load_dwordx2 v[100:101], v[16:17], off offset:64
	global_load_dwordx2 v[94:95], v[14:15], off
	global_load_dwordx2 v[98:99], v[12:13], off
	v_cndmask_b32_e64 v12, v38, v126, s[44:45]
	v_ashrrev_i32_e32 v13, 31, v12
	v_lshlrev_b64 v[14:15], 11, v[12:13]
	s_mul_i32 s0, s3, 40
	v_lshl_add_u64 v[14:15], v[46:47], 0, v[14:15]
	v_lshlrev_b64 v[16:17], 7, v[12:13]
	v_lshlrev_b64 v[12:13], 6, v[12:13]
	v_add_u32_e32 v125, s0, v38
	v_lshl_add_u64 v[16:17], v[52:53], 0, v[16:17]
	global_load_dwordx4 v[20:23], v[14:15], off
	global_load_dwordx2 v[88:89], v[16:17], off
	v_lshl_add_u64 v[14:15], v[48:49], 0, v[12:13]
	v_lshl_add_u64 v[12:13], v[50:51], 0, v[12:13]
	v_cmp_gt_i32_e64 s[42:43], s4, v125
	global_load_dwordx2 v[92:93], v[16:17], off offset:64
	global_load_dwordx2 v[86:87], v[14:15], off
	global_load_dwordx2 v[90:91], v[12:13], off
	v_cndmask_b32_e64 v12, v38, v125, s[42:43]
	s_mul_i32 s0, s3, 48
	v_ashrrev_i32_e32 v13, 31, v12
	v_add_u32_e32 v124, s0, v38
	s_mul_i32 s0, s3, 56
	v_lshlrev_b64 v[14:15], 11, v[12:13]
	v_cmp_gt_i32_e64 s[40:41], s4, v124
	v_add_u32_e32 v123, s0, v38
	v_lshl_add_u64 v[14:15], v[46:47], 0, v[14:15]
	v_lshlrev_b64 v[16:17], 7, v[12:13]
	v_lshlrev_b64 v[12:13], 6, v[12:13]
	v_cndmask_b32_e64 v68, v38, v124, s[40:41]
	v_cmp_gt_i32_e64 s[38:39], s4, v123
	v_lshl_add_u64 v[64:65], v[52:53], 0, v[16:17]
	global_load_dwordx4 v[16:19], v[14:15], off
	global_load_dwordx2 v[80:81], v[64:65], off
	v_lshl_add_u64 v[14:15], v[48:49], 0, v[12:13]
	v_ashrrev_i32_e32 v69, 31, v68
	v_cndmask_b32_e64 v136, v38, v123, s[38:39]
	v_lshl_add_u64 v[12:13], v[50:51], 0, v[12:13]
	global_load_dwordx2 v[84:85], v[64:65], off offset:64
	global_load_dwordx2 v[78:79], v[14:15], off
	global_load_dwordx2 v[82:83], v[12:13], off
	v_lshlrev_b64 v[14:15], 7, v[68:69]
	v_ashrrev_i32_e32 v137, 31, v136
	v_lshl_add_u64 v[72:73], v[52:53], 0, v[14:15]
	v_lshlrev_b64 v[14:15], 7, v[136:137]
	v_lshl_add_u64 v[138:139], v[52:53], 0, v[14:15]
	v_lshlrev_b64 v[14:15], 6, v[136:137]
	s_mov_b32 s0, 0x2e00000
	v_lshl_add_u64 v[64:65], v[48:49], 0, v[14:15]
	v_lshl_add_u64 v[14:15], v[50:51], 0, v[14:15]
	v_add_co_u32_e32 v70, vcc, s0, v62
	v_lshlrev_b64 v[12:13], 11, v[68:69]
	s_nop 0
	v_addc_co_u32_e32 v71, vcc, 0, v63, vcc
	global_load_dwordx2 v[66:67], v[138:139], off offset:64
	global_load_dwordx2 v[62:63], v[64:65], off
	s_nop 0
	global_load_dwordx2 v[64:65], v[14:15], off
	global_load_dwordx2 v[140:141], v[70:71], off
	v_lshl_add_u64 v[12:13], v[46:47], 0, v[12:13]
	s_waitcnt vmcnt(0)
	v_and_b32_e32 v145, 0xffff0000, v10
	v_and_b32_e32 v144, 0xffff0000, v8
	v_and_b32_e32 v149, 0xffff0000, v11
	v_and_b32_e32 v148, 0xffff0000, v9
	v_lshlrev_b32_e32 v143, 16, v10
	v_lshlrev_b32_e32 v142, 16, v8
	v_lshlrev_b32_e32 v147, 16, v11
	v_lshlrev_b32_e32 v146, 16, v9
	v_pk_mul_f32 v[8:9], v[144:145], v[144:145]
	v_pk_mul_f32 v[10:11], v[148:149], v[148:149]
	v_pk_fma_f32 v[8:9], v[142:143], v[142:143], v[8:9]
	v_pk_fma_f32 v[10:11], v[146:147], v[146:147], v[10:11]
	v_mov_b32_e32 v14, v133
	v_mov_b32_e32 v15, v135
	v_pk_add_f32 v[8:9], v[8:9], v[10:11]
	v_mov_b32_e32 v10, v132
	v_mov_b32_e32 v11, v134
	v_pk_mul_f32 v[14:15], v[14:15], v[14:15]
	v_add_f32_e32 v8, v8, v9
	v_pk_fma_f32 v[10:11], v[10:11], v[10:11], v[14:15]
	global_load_dwordx4 v[12:15], v[12:13], off
	s_nop 0
	global_load_dwordx2 v[70:71], v[72:73], off
	v_add_f32_e32 v8, v11, v8
	v_add_f32_e32 v61, v10, v8
	ds_bpermute_b32 v74, v119, v61
	v_lshlrev_b64 v[8:9], 6, v[68:69]
	v_lshl_add_u64 v[10:11], v[48:49], 0, v[8:9]
	v_lshl_add_u64 v[8:9], v[50:51], 0, v[8:9]
	v_pk_mul_f32 v[132:133], v[44:45], v[132:133]
	s_waitcnt lgkmcnt(0)
; __device__ __forceinline__ unsigned cvt_pk(float lo, float hi) { unsigned r; asm volatile("v_cvt_pk_bf16_f32 %0, %1, %2" : "=v"(r) : "v"(lo), "v"(hi)); return r; }
; __device__ __forceinline__ float sq4(f32x4 a) { return (a.x * a.x + a.y * a.y) + (a.z * a.z + a.w * a.w); }
; __device__ __forceinline__ u32x4 pack8(f32x4 a, f32x4 b) { u32x4 o; o.x = cvt_pk(a.x, a.y); o.y = cvt_pk(a.z, a.w); o.z = cvt_pk(b.x, b.y); o.w = cvt_pk(b.z, b.w); return o; }
; __device__ __forceinline__ void finalize_phase(const Params& p, LAS unsigned char* lds, int G) {
;     ...
;                     float ss = sq4(a0) + sq4(a1) + (x1.x * x1.x + x1.y * x1.y) + (x2.x * x2.x + x2.y * x2.y);
;                     ss += __shfl_xor(ss, 1); ss += __shfl_xor(ss, 2); ss += __shfl_xor(ss, 4);
;                     const float r = 1.0f / sqrtf(ss * (1.f / 96.f) + EPS);
;                     a0 = a0 * gka * r; a1 = a1 * gkb * r; x1 = x1 * gk1 * r; x2 = x2 * gk2 * r;
;                     const f32x2 o1 = x1 * cs - x2 * sn, o2 = x2 * cs + x1 * sn;
;                     *(u32x4*)(KF + orow + 8 * sub) = pack8(a0, a1);
;                     *(unsigned*)(KF + orow + 64 + 2 * sub) = cvt_pk(o1.x, o1.y); *(unsigned*)(KF + orow + 80 + 2 * sub) = cvt_pk(o2.x, o2.y);
;                 }
	v_add_f32_e32 v61, v61, v74
	ds_bpermute_b32 v68, v120, v61
	global_load_dwordx2 v[76:77], v[72:73], off offset:64
	s_nop 0
	global_load_dwordx2 v[72:73], v[10:11], off
	global_load_dwordx2 v[74:75], v[8:9], off
	v_lshlrev_b64 v[8:9], 11, v[136:137]
	v_lshl_add_u64 v[8:9], v[46:47], 0, v[8:9]
	v_pk_mul_f32 v[134:135], v[42:43], v[134:135]
	s_waitcnt lgkmcnt(0)
	v_add_f32_e32 v61, v61, v68
	global_load_dwordx4 v[8:11], v[8:9], off
	s_nop 0
	global_load_dwordx2 v[68:69], v[138:139], off
	ds_bpermute_b32 v136, v121, v61
	s_waitcnt lgkmcnt(0)
	v_add_f32_e32 v61, v61, v136
	v_fmamk_f32 v61, v61, 0x3c2aaaab, v39
	v_rsq_f32_e32 v138, v61
	s_nop 0
	v_ashrrev_i32_e32 v136, 9, v38
	v_and_or_b32 v136, v136, -8, v37
	v_ashrrev_i32_e32 v137, 31, v136
	v_lshlrev_b64 v[136:137], 12, v[136:137]
	v_and_or_b32 v152, v38, s8, v136
	v_mov_b32_e32 v136, v138
	v_mov_b32_e32 v138, v142
	v_mov_b32_e32 v139, v144
	v_pk_mul_f32 v[132:133], v[132:133], v[136:137] op_sel_hi:[1,0]
	v_pk_mul_f32 v[138:139], v[4:5], v[138:139]
	v_mov_b32_e32 v150, v146
	v_mov_b32_e32 v151, v148
	v_mov_b32_e32 v148, v147
	v_pk_mul_f32 v[134:135], v[134:135], v[136:137] op_sel_hi:[1,0]
	v_pk_mul_f32 v[146:147], v[140:141], v[132:133]
	v_pk_mul_f32 v[138:139], v[138:139], v[136:137] op_sel_hi:[1,0]
	v_pk_fma_f32 v[146:147], v[130:131], v[134:135], v[146:147] neg_lo:[0,0,1] neg_hi:[0,0,1]
	v_pk_mul_f32 v[134:135], v[140:141], v[134:135]
	v_mov_b32_e32 v144, v143
	v_pk_fma_f32 v[134:135], v[130:131], v[132:133], v[134:135]
	v_cvt_pk_bf16_f32 v130, v138, v139
	v_mov_b64_e32 v[138:139], s[36:37]
	v_mad_u64_u32 v[138:139], s[0:1], v152, s10, v[138:139]
	v_pk_mul_f32 v[150:151], v[6:7], v[150:151]
	v_pk_mul_f32 v[142:143], v[0:1], v[144:145]
	v_pk_mul_f32 v[144:145], v[2:3], v[148:149]
	v_mad_i32_i24 v139, v137, s10, v139
	v_pk_mul_f32 v[150:151], v[150:151], v[136:137] op_sel_hi:[1,0]
	v_pk_mul_f32 v[144:145], v[144:145], v[136:137] op_sel_hi:[1,0]
	v_pk_mul_f32 v[142:143], v[142:143], v[136:137] op_sel_hi:[1,0]
	v_cvt_pk_bf16_f32 v131, v150, v151
	v_lshl_add_u64 v[136:137], v[138:139], 0, v[40:41]
	v_cvt_pk_bf16_f32 v132, v142, v143
	v_mov_b32_e32 v61, v41
	v_cvt_pk_bf16_f32 v133, v144, v145
	global_store_dwordx4 v[136:137], v[130:133], off
	s_nop 1
	v_cvt_pk_bf16_f32 v132, v146, v147
	v_lshl_add_u64 v[130:131], v[138:139], 0, v[60:61]
	global_store_dword v[130:131], v132, off offset:128
	v_cvt_pk_bf16_f32 v132, v134, v135
	global_store_dword v[130:131], v132, off offset:160
	s_and_saveexec_b64 s[52:53], s[50:51]
	s_cbranch_execz .LBB0_562
	v_lshlrev_b32_e32 v131, 16, v34
	v_and_b32_e32 v133, 0xffff0000, v34
	v_and_b32_e32 v132, 0xffff0000, v32
	v_lshlrev_b32_e32 v135, 16, v35
	v_and_b32_e32 v35, 0xffff0000, v35
	v_and_b32_e32 v34, 0xffff0000, v33
	v_lshlrev_b32_e32 v130, 16, v32
	v_lshlrev_b32_e32 v134, 16, v33
	v_pk_mul_f32 v[32:33], v[132:133], v[132:133]
	v_pk_mul_f32 v[136:137], v[34:35], v[34:35]
	v_pk_fma_f32 v[32:33], v[130:131], v[130:131], v[32:33]
	v_pk_fma_f32 v[136:137], v[134:135], v[134:135], v[136:137]
	v_mov_b32_e32 v138, v117
	v_mov_b32_e32 v139, v111
	v_pk_add_f32 v[32:33], v[32:33], v[136:137]
	v_mov_b32_e32 v136, v116
	v_mov_b32_e32 v137, v110
	v_pk_mul_f32 v[138:139], v[138:139], v[138:139]
	v_add_f32_e32 v32, v32, v33
	v_pk_fma_f32 v[136:137], v[136:137], v[136:137], v[138:139]
	v_mov_b32_e32 v141, v34
	v_add_f32_e32 v32, v137, v32
	v_add_f32_e32 v32, v136, v32
	ds_bpermute_b32 v33, v119, v32
	v_mov_b32_e32 v34, v135
	v_pk_mul_f32 v[34:35], v[2:3], v[34:35]
	v_pk_mul_f32 v[110:111], v[42:43], v[110:111]
	v_pk_mul_f32 v[116:117], v[44:45], v[116:117]
	s_waitcnt lgkmcnt(0)
	v_add_f32_e32 v32, v32, v33
	ds_bpermute_b32 v33, v120, v32
	s_waitcnt lgkmcnt(0)
	v_add_f32_e32 v32, v32, v33
	ds_bpermute_b32 v33, v121, v32
	s_waitcnt lgkmcnt(0)
	v_add_f32_e32 v32, v32, v33
	v_fmamk_f32 v32, v32, 0x3c2aaaab, v39
	v_rsq_f32_e32 v138, v32
	s_nop 0
	v_ashrrev_i32_e32 v32, 9, v129
	v_and_or_b32 v32, v32, -8, v37
	v_ashrrev_i32_e32 v33, 31, v32
	v_lshlrev_b64 v[136:137], 12, v[32:33]
	v_and_or_b32 v129, v129, s8, v136
	v_mov_b32_e32 v32, v138
	v_mov_b32_e32 v138, v130
	v_mov_b32_e32 v139, v132
	v_mov_b32_e32 v140, v134
	v_mov_b32_e32 v132, v131
	v_pk_mul_f32 v[138:139], v[4:5], v[138:139]
	v_pk_mul_f32 v[140:141], v[6:7], v[140:141]
	v_pk_mul_f32 v[130:131], v[0:1], v[132:133]
	v_pk_mul_f32 v[140:141], v[140:141], v[32:33] op_sel_hi:[1,0]
	v_pk_mul_f32 v[138:139], v[138:139], v[32:33] op_sel_hi:[1,0]
	v_pk_mul_f32 v[132:133], v[34:35], v[32:33] op_sel_hi:[1,0]
	v_pk_mul_f32 v[34:35], v[130:131], v[32:33] op_sel_hi:[1,0]
	v_pk_mul_f32 v[110:111], v[110:111], v[32:33] op_sel_hi:[1,0]
	v_pk_mul_f32 v[32:33], v[116:117], v[32:33] op_sel_hi:[1,0]
	s_nop 0
	v_pk_mul_f32 v[116:117], v[114:115], v[32:33]
	s_nop 0
	v_pk_fma_f32 v[116:117], v[112:113], v[110:111], v[116:117] neg_lo:[0,0,1] neg_hi:[0,0,1]
	v_pk_mul_f32 v[110:111], v[114:115], v[110:111]
	s_nop 0
	v_pk_fma_f32 v[110:111], v[112:113], v[32:33], v[110:111]
	v_mov_b64_e32 v[112:113], s[36:37]
	v_mad_u64_u32 v[112:113], s[0:1], v129, s10, v[112:113]
	v_mad_i32_i24 v113, v137, s10, v113
	v_cvt_pk_bf16_f32 v32, v138, v139
	v_cvt_pk_bf16_f32 v33, v140, v141
	v_cvt_pk_bf16_f32 v34, v34, v35
	v_lshl_add_u64 v[114:115], v[112:113], 0, v[40:41]
	v_cvt_pk_bf16_f32 v35, v132, v133
	global_store_dwordx4 v[114:115], v[32:35], off
	s_nop 1
	v_cvt_pk_bf16_f32 v34, v116, v117
	v_lshl_add_u64 v[32:33], v[112:113], 0, v[60:61]
	global_store_dword v[32:33], v34, off offset:128
	v_cvt_pk_bf16_f32 v34, v110, v111
	global_store_dword v[32:33], v34, off offset:160
	s_or_b64 exec, exec, s[52:53]
	s_and_saveexec_b64 s[50:51], s[48:49]
	s_cbranch_execnz .LBB0_563
